# grid barrier: XCD leader bumps the per-XCD generation (releases its blocks) before running its own buffer_inv
# speedup vs baseline: 1.0024x; 1.0005x over previous
.LBB0_167:
	s_or_b64 exec, exec, s[8:9]
	v_readlane_b32 s0, v251, 54
	v_readlane_b32 s1, v251, 55
	s_waitcnt vmcnt(0)
	s_nop 3
	global_atomic_add v171, v173, s[0:1]
	buffer_inv sc1
	s_waitcnt vmcnt(0)
